# prompt attention epilogue: 16 dwordx2 stores per lane widened to 8 dwordx4 via v_permlane32_swap (on fused far-chunk version)
# speedup vs baseline: 1.0151x; 1.0041x over previous
.LBB0_73:
	v_readlane_b32 s0, v247, 23
	v_readlane_b32 s1, v247, 24
	s_and_b64 vcc, exec, s[0:1]
	s_cbranch_vccz .LBB0_101
	s_waitcnt vmcnt(0)
	v_ashrrev_i32_e32 v2, 3, v222
	v_ashrrev_i32_e32 v3, 31, v2
	v_and_b32_e32 v5, 64, v191
	v_lshlrev_b64 v[146:147], 13, v[2:3]
	v_xor_b32_e32 v3, 32, v191
	v_add_u32_e32 v5, 64, v5
	s_movk_i32 s0, 0xc0
	v_lshlrev_b32_e32 v4, 3, v222
	v_cmp_lt_i32_e32 vcc, v3, v5
	v_cmp_gt_i32_e64 s[4:5], s0, v222
	v_ashrrev_i32_e32 v168, 4, v222
	v_and_b32_e32 v0, 0x78, v4
	s_mov_b64 s[0:1], 0x80000
	v_cndmask_b32_e32 v3, v191, v3, vcc
	v_and_b32_e32 v4, 56, v4
	v_lshl_add_u64 v[150:151], v[146:147], 0, s[0:1]
	v_lshlrev_b32_e32 v170, 2, v3
	s_movk_i32 s0, 0x90
	v_mul_lo_u32 v3, v168, s97
	v_lshlrev_b32_e32 v5, 1, v0
	s_add_u32 s2, s16, 0x20900000
	v_add3_u32 v173, 0, v3, v5
	v_mul_lo_u32 v2, v2, s0
	v_and_b32_e32 v3, 48, v4
	v_and_b32_e32 v5, 8, v4
	v_lshl_or_b32 v3, v3, 1, v5
	v_lshl_add_u32 v176, v155, 4, 0
	s_addc_u32 s3, s17, 0
	s_lshl_b32 s6, s62, 5
	v_add3_u32 v174, 0, v2, v3
	v_sub_u32_e32 v177, v176, v154
	s_ashr_i32 s18, s56, 7
	v_lshlrev_b32_e32 v167, 4, v222
	v_and_or_b32 v169, s6, 32, v149
	v_mul_u32_u24_e32 v171, 0x90, v149
	v_mad_u32_u24 v172, v149, s0, v220
	v_add_u32_e32 v175, 0x2400, v174
	v_mad_u32_u24 v180, v149, s0, v176
	v_add_u32_e32 v181, 0xc0, v168
	v_lshlrev_b32_e32 v0, 1, v0
	v_lshlrev_b32_e32 v152, 1, v4
	v_lshlrev_b32_e32 v154, 1, v154
	v_lshlrev_b32_e32 v156, 2, v148
	v_readlane_b32 s19, v247, 22
	s_branch .LBB0_76
.LBB0_75:
	ds_bpermute_b32 v68, v170, v153
	v_lshl_add_u64 v[66:67], v[158:159], 1, s[48:49]
	s_lshl_b32 s88, s20, 1
	v_lshl_add_u64 v[66:67], v[66:67], 0, s[88:89]
	v_mov_b32_e32 v157, v1
	s_waitcnt lgkmcnt(0)
	v_add_f32_e32 v68, v153, v68
	v_div_scale_f32 v69, s[0:1], v68, v68, 1.0
	v_rcp_f32_e32 v70, v69
	v_div_scale_f32 v71, vcc, 1.0, v68, 1.0
	v_lshl_add_u64 v[66:67], v[66:67], 0, v[156:157]
	v_fma_f32 v72, -v69, v70, 1.0
	v_fmac_f32_e32 v70, v72, v70
	v_mul_f32_e32 v72, v71, v70
	v_fma_f32 v73, -v69, v72, v71
	v_fmac_f32_e32 v72, v73, v70
	v_fma_f32 v69, -v69, v72, v71
	v_div_fmas_f32 v69, v69, v70, v72
	v_div_fixup_f32 v68, v69, v68, 1.0
	v_pk_mul_f32 v[50:51], v[50:51], v[68:69] op_sel_hi:[1,0]
	v_pk_mul_f32 v[52:53], v[52:53], v[68:69] op_sel_hi:[1,0]
	v_pk_mul_f32 v[54:55], v[54:55], v[68:69] op_sel_hi:[1,0]
	v_pk_mul_f32 v[56:57], v[56:57], v[68:69] op_sel_hi:[1,0]
	v_pk_mul_f32 v[58:59], v[58:59], v[68:69] op_sel_hi:[1,0]
	v_pk_mul_f32 v[60:61], v[60:61], v[68:69] op_sel_hi:[1,0]
	v_pk_mul_f32 v[62:63], v[62:63], v[68:69] op_sel_hi:[1,0]
	v_pk_mul_f32 v[64:65], v[64:65], v[68:69] op_sel_hi:[1,0]
	v_pk_mul_f32 v[34:35], v[34:35], v[68:69] op_sel_hi:[1,0]
	v_pk_mul_f32 v[36:37], v[36:37], v[68:69] op_sel_hi:[1,0]
	v_pk_mul_f32 v[38:39], v[38:39], v[68:69] op_sel_hi:[1,0]
	v_pk_mul_f32 v[40:41], v[40:41], v[68:69] op_sel_hi:[1,0]
	v_pk_mul_f32 v[42:43], v[42:43], v[68:69] op_sel_hi:[1,0]
	v_pk_mul_f32 v[44:45], v[44:45], v[68:69] op_sel_hi:[1,0]
	v_pk_mul_f32 v[46:47], v[46:47], v[68:69] op_sel_hi:[1,0]
	v_pk_mul_f32 v[48:49], v[48:49], v[68:69] op_sel_hi:[1,0]
	v_pk_mul_f32 v[18:19], v[18:19], v[68:69] op_sel_hi:[1,0]
	v_pk_mul_f32 v[20:21], v[20:21], v[68:69] op_sel_hi:[1,0]
	v_pk_mul_f32 v[22:23], v[22:23], v[68:69] op_sel_hi:[1,0]
	v_pk_mul_f32 v[24:25], v[24:25], v[68:69] op_sel_hi:[1,0]
	v_pk_mul_f32 v[26:27], v[26:27], v[68:69] op_sel_hi:[1,0]
	v_pk_mul_f32 v[28:29], v[28:29], v[68:69] op_sel_hi:[1,0]
	v_pk_mul_f32 v[30:31], v[30:31], v[68:69] op_sel_hi:[1,0]
	v_pk_mul_f32 v[32:33], v[32:33], v[68:69] op_sel_hi:[1,0]
	v_pk_mul_f32 v[2:3], v[2:3], v[68:69] op_sel_hi:[1,0]
	v_pk_mul_f32 v[4:5], v[4:5], v[68:69] op_sel_hi:[1,0]
	v_pk_mul_f32 v[6:7], v[6:7], v[68:69] op_sel_hi:[1,0]
	v_pk_mul_f32 v[8:9], v[8:9], v[68:69] op_sel_hi:[1,0]
	v_pk_mul_f32 v[10:11], v[10:11], v[68:69] op_sel_hi:[1,0]
	v_pk_mul_f32 v[12:13], v[12:13], v[68:69] op_sel_hi:[1,0]
	v_pk_mul_f32 v[14:15], v[14:15], v[68:69] op_sel_hi:[1,0]
	v_pk_mul_f32 v[16:17], v[16:17], v[68:69] op_sel_hi:[1,0]
	v_cvt_pk_bf16_f32 v50, v50, v51
	v_cvt_pk_bf16_f32 v51, v52, v53
	v_cvt_pk_bf16_f32 v52, v54, v55
	v_cvt_pk_bf16_f32 v53, v56, v57
	v_cvt_pk_bf16_f32 v58, v58, v59
	v_cvt_pk_bf16_f32 v59, v60, v61
	v_cvt_pk_bf16_f32 v60, v62, v63
	v_cvt_pk_bf16_f32 v61, v64, v65
	v_cvt_pk_bf16_f32 v34, v34, v35
	v_cvt_pk_bf16_f32 v35, v36, v37
	v_cvt_pk_bf16_f32 v36, v38, v39
	v_cvt_pk_bf16_f32 v37, v40, v41
	v_cvt_pk_bf16_f32 v42, v42, v43
	v_cvt_pk_bf16_f32 v43, v44, v45
	v_cvt_pk_bf16_f32 v44, v46, v47
	v_cvt_pk_bf16_f32 v45, v48, v49
	v_cvt_pk_bf16_f32 v18, v18, v19
	v_cvt_pk_bf16_f32 v19, v20, v21
	v_cvt_pk_bf16_f32 v20, v22, v23
	v_cvt_pk_bf16_f32 v21, v24, v25
	v_cvt_pk_bf16_f32 v26, v26, v27
	v_cvt_pk_bf16_f32 v27, v28, v29
	v_cvt_pk_bf16_f32 v28, v30, v31
	v_cvt_pk_bf16_f32 v29, v32, v33
	v_cvt_pk_bf16_f32 v2, v2, v3
	v_cvt_pk_bf16_f32 v3, v4, v5
	v_cvt_pk_bf16_f32 v4, v6, v7
	v_cvt_pk_bf16_f32 v5, v8, v9
	v_cvt_pk_bf16_f32 v10, v10, v11
	v_cvt_pk_bf16_f32 v11, v12, v13
	v_cvt_pk_bf16_f32 v12, v14, v15
	v_cvt_pk_bf16_f32 v13, v16, v17
	s_nop 1
	v_permlane32_swap_b32_e32 v50, v52
	v_permlane32_swap_b32_e32 v51, v53
	v_permlane32_swap_b32_e32 v58, v60
	v_permlane32_swap_b32_e32 v59, v61
	v_permlane32_swap_b32_e32 v34, v36
	v_permlane32_swap_b32_e32 v35, v37
	v_permlane32_swap_b32_e32 v42, v44
	v_permlane32_swap_b32_e32 v43, v45
	v_permlane32_swap_b32_e32 v18, v20
	v_permlane32_swap_b32_e32 v19, v21
	v_permlane32_swap_b32_e32 v26, v28
	v_permlane32_swap_b32_e32 v27, v29
	v_permlane32_swap_b32_e32 v2, v4
	v_permlane32_swap_b32_e32 v3, v5
	v_permlane32_swap_b32_e32 v10, v12
	v_permlane32_swap_b32_e32 v11, v13
	s_add_i32 s19, s19, s36
	s_cmpk_gt_i32 s19, 0x1ff
	global_store_dwordx4 v[66:67], v[50:53], off
	global_store_dwordx4 v[66:67], v[58:61], off offset:32
	global_store_dwordx4 v[66:67], v[34:37], off offset:64
	global_store_dwordx4 v[66:67], v[42:45], off offset:96
	global_store_dwordx4 v[66:67], v[18:21], off offset:128
	global_store_dwordx4 v[66:67], v[26:29], off offset:160
	global_store_dwordx4 v[66:67], v[2:5], off offset:192
	global_store_dwordx4 v[66:67], v[10:13], off offset:224
	s_cbranch_scc1 .LBB0_101
